# v59 + sample-stream attention items publish their outputs with write-through stores (no L2 write-back mid-phase)
# baseline (speedup 1.0000x reference)
.Lat3_epi_a:
	v_mov_b32_e32 v15, v175
	s_nop 1
	v_permlane32_swap_b32_e32 v175, v15
	v_add_f32_e32 v175, v175, v15
	v_div_scale_f32 v2, s[16:17], v175, v175, 1.0
	v_div_scale_f32 v4, vcc, 1.0, v175, 1.0
	v_rcp_f32_e32 v3, v2
	s_nop 1
	v_fma_f32 v5, -v2, v3, 1.0
	v_fmac_f32_e32 v3, v5, v3
	v_mul_f32_e32 v5, v4, v3
	v_fma_f32 v213, -v2, v5, v4
	v_fmac_f32_e32 v5, v213, v3
	v_fma_f32 v2, -v2, v5, v4
	v_div_fmas_f32 v2, v2, v3, v5
	v_div_fixup_f32 v0, v2, v175, 1.0
	s_nop 4
	v_mul_f32_e32 v64, v64, v0
	v_mul_f32_e32 v65, v65, v0
	v_mul_f32_e32 v66, v66, v0
	v_mul_f32_e32 v67, v67, v0
	v_mul_f32_e32 v68, v68, v0
	v_mul_f32_e32 v69, v69, v0
	v_mul_f32_e32 v70, v70, v0
	v_mul_f32_e32 v71, v71, v0
	v_cvt_pk_bf16_f32 v6, v64, v65
	v_cvt_pk_bf16_f32 v7, v66, v67
	v_cvt_pk_bf16_f32 v8, v68, v69
	v_cvt_pk_bf16_f32 v9, v70, v71
	s_nop 1
	s_waitcnt vmcnt(23)
	v_mfma_f32_32x32x16_bf16 v[232:247], v[148:151], v[6:9], 0
	s_waitcnt vmcnt(22)
	v_mfma_f32_32x32x16_bf16 v[96:111], v[144:147], v[6:9], 0
	v_mul_f32_e32 v72, v72, v0
	v_mul_f32_e32 v73, v73, v0
	v_mul_f32_e32 v74, v74, v0
	v_mul_f32_e32 v75, v75, v0
	v_mul_f32_e32 v76, v76, v0
	v_mul_f32_e32 v77, v77, v0
	v_mul_f32_e32 v78, v78, v0
	v_mul_f32_e32 v79, v79, v0
	v_cvt_pk_bf16_f32 v10, v72, v73
	v_cvt_pk_bf16_f32 v11, v74, v75
	v_cvt_pk_bf16_f32 v12, v76, v77
	v_cvt_pk_bf16_f32 v13, v78, v79
	s_nop 1
	s_waitcnt vmcnt(21)
	v_mfma_f32_32x32x16_bf16 v[232:247], v[140:143], v[10:13], v[232:247]
	s_waitcnt vmcnt(20)
	v_mfma_f32_32x32x16_bf16 v[96:111], v[136:139], v[10:13], v[96:111]
	v_mul_f32_e32 v48, v48, v0
	v_mul_f32_e32 v49, v49, v0
	v_mul_f32_e32 v50, v50, v0
	v_mul_f32_e32 v51, v51, v0
	v_mul_f32_e32 v52, v52, v0
	v_mul_f32_e32 v53, v53, v0
	v_mul_f32_e32 v54, v54, v0
	v_mul_f32_e32 v55, v55, v0
	v_cvt_pk_bf16_f32 v6, v48, v49
	v_cvt_pk_bf16_f32 v7, v50, v51
	v_cvt_pk_bf16_f32 v8, v52, v53
	v_cvt_pk_bf16_f32 v9, v54, v55
	s_nop 1
	s_waitcnt vmcnt(19)
	v_mfma_f32_32x32x16_bf16 v[232:247], v[132:135], v[6:9], v[232:247]
	s_waitcnt vmcnt(18)
	v_mfma_f32_32x32x16_bf16 v[96:111], v[128:131], v[6:9], v[96:111]
	v_mul_f32_e32 v56, v56, v0
	v_mul_f32_e32 v57, v57, v0
	v_mul_f32_e32 v58, v58, v0
	v_mul_f32_e32 v59, v59, v0
	v_mul_f32_e32 v60, v60, v0
	v_mul_f32_e32 v61, v61, v0
	v_mul_f32_e32 v62, v62, v0
	v_mul_f32_e32 v63, v63, v0
	v_cvt_pk_bf16_f32 v10, v56, v57
	v_cvt_pk_bf16_f32 v11, v58, v59
	v_cvt_pk_bf16_f32 v12, v60, v61
	v_cvt_pk_bf16_f32 v13, v62, v63
	s_nop 1
	s_waitcnt vmcnt(17)
	v_mfma_f32_32x32x16_bf16 v[232:247], v[124:127], v[10:13], v[232:247]
	s_waitcnt vmcnt(16)
	v_mfma_f32_32x32x16_bf16 v[96:111], v[120:123], v[10:13], v[96:111]
	v_mul_f32_e32 v32, v32, v0
	v_mul_f32_e32 v33, v33, v0
	v_mul_f32_e32 v34, v34, v0
	v_mul_f32_e32 v35, v35, v0
	v_mul_f32_e32 v36, v36, v0
	v_mul_f32_e32 v37, v37, v0
	v_mul_f32_e32 v38, v38, v0
	v_mul_f32_e32 v39, v39, v0
	v_cvt_pk_bf16_f32 v6, v32, v33
	v_cvt_pk_bf16_f32 v7, v34, v35
	v_cvt_pk_bf16_f32 v8, v36, v37
	v_cvt_pk_bf16_f32 v9, v38, v39
	s_nop 1
	s_waitcnt vmcnt(15)
	v_mfma_f32_32x32x16_bf16 v[232:247], v[116:119], v[6:9], v[232:247]
	s_waitcnt vmcnt(14)
	v_mfma_f32_32x32x16_bf16 v[96:111], v[112:115], v[6:9], v[96:111]
	v_mul_f32_e32 v40, v40, v0
	v_mul_f32_e32 v41, v41, v0
	v_mul_f32_e32 v42, v42, v0
	v_mul_f32_e32 v43, v43, v0
	v_mul_f32_e32 v44, v44, v0
	v_mul_f32_e32 v45, v45, v0
	v_mul_f32_e32 v46, v46, v0
	v_mul_f32_e32 v47, v47, v0
	v_cvt_pk_bf16_f32 v10, v40, v41
	v_cvt_pk_bf16_f32 v11, v42, v43
	v_cvt_pk_bf16_f32 v12, v44, v45
	v_cvt_pk_bf16_f32 v13, v46, v47
	s_nop 1
	s_waitcnt vmcnt(13)
	v_mfma_f32_32x32x16_bf16 v[232:247], v[220:223], v[10:13], v[232:247]
	s_waitcnt vmcnt(12)
	v_mfma_f32_32x32x16_bf16 v[96:111], v[224:227], v[10:13], v[96:111]
	v_mul_f32_e32 v16, v16, v0
	v_mul_f32_e32 v17, v17, v0
	v_mul_f32_e32 v18, v18, v0
	v_mul_f32_e32 v19, v19, v0
	v_mul_f32_e32 v20, v20, v0
	v_mul_f32_e32 v21, v21, v0
	v_mul_f32_e32 v22, v22, v0
	v_mul_f32_e32 v23, v23, v0
	v_cvt_pk_bf16_f32 v6, v16, v17
	v_cvt_pk_bf16_f32 v7, v18, v19
	v_cvt_pk_bf16_f32 v8, v20, v21
	v_cvt_pk_bf16_f32 v9, v22, v23
	s_nop 1
	s_waitcnt vmcnt(11)
	v_mfma_f32_32x32x16_bf16 v[232:247], v[228:231], v[6:9], v[232:247]
	s_waitcnt vmcnt(10)
	v_mfma_f32_32x32x16_bf16 v[96:111], v[80:83], v[6:9], v[96:111]
	v_mul_f32_e32 v24, v24, v0
	v_mul_f32_e32 v25, v25, v0
	v_mul_f32_e32 v26, v26, v0
	v_mul_f32_e32 v27, v27, v0
	v_mul_f32_e32 v28, v28, v0
	v_mul_f32_e32 v29, v29, v0
	v_mul_f32_e32 v30, v30, v0
	v_mul_f32_e32 v31, v31, v0
	v_cvt_pk_bf16_f32 v10, v24, v25
	v_cvt_pk_bf16_f32 v11, v26, v27
	v_cvt_pk_bf16_f32 v12, v28, v29
	v_cvt_pk_bf16_f32 v13, v30, v31
	s_nop 1
	s_waitcnt vmcnt(9)
	v_mfma_f32_32x32x16_bf16 v[232:247], v[84:87], v[10:13], v[232:247]
	s_waitcnt vmcnt(8)
	v_mfma_f32_32x32x16_bf16 v[96:111], v[88:91], v[10:13], v[96:111]
	v_cmp_gt_u32_e32 vcc, s76, v167
	s_and_saveexec_b64 s[6:7], vcc
	s_cbranch_execz .LBB0_470
	s_nop 10
	s_waitcnt vmcnt(7)
	v_lshlrev_b32_e32 v2, 16, v190
	v_and_b32_e32 v3, 0xffff0000, v190
	v_lshlrev_b32_e32 v4, 16, v191
	v_and_b32_e32 v5, 0xffff0000, v191
	v_mul_f32_e32 v232, v232, v2
	v_mul_f32_e32 v233, v233, v3
	v_mul_f32_e32 v234, v234, v4
	v_mul_f32_e32 v235, v235, v5
	v_cvt_pk_bf16_f32 v190, v232, v233
	v_cvt_pk_bf16_f32 v191, v234, v235
	s_waitcnt vmcnt(6)
	v_lshlrev_b32_e32 v2, 16, v192
	v_and_b32_e32 v3, 0xffff0000, v192
	v_lshlrev_b32_e32 v4, 16, v193
	v_and_b32_e32 v5, 0xffff0000, v193
	v_mul_f32_e32 v236, v236, v2
	v_mul_f32_e32 v237, v237, v3
	v_mul_f32_e32 v238, v238, v4
	v_mul_f32_e32 v239, v239, v5
	v_cvt_pk_bf16_f32 v192, v236, v237
	v_cvt_pk_bf16_f32 v193, v238, v239
	s_waitcnt vmcnt(5)
	v_lshlrev_b32_e32 v2, 16, v194
	v_and_b32_e32 v3, 0xffff0000, v194
	v_lshlrev_b32_e32 v4, 16, v195
	v_and_b32_e32 v5, 0xffff0000, v195
	v_mul_f32_e32 v240, v240, v2
	v_mul_f32_e32 v241, v241, v3
	v_mul_f32_e32 v242, v242, v4
	v_mul_f32_e32 v243, v243, v5
	v_cvt_pk_bf16_f32 v194, v240, v241
	v_cvt_pk_bf16_f32 v195, v242, v243
	s_waitcnt vmcnt(4)
	v_lshlrev_b32_e32 v2, 16, v198
	v_and_b32_e32 v3, 0xffff0000, v198
	v_lshlrev_b32_e32 v4, 16, v199
	v_and_b32_e32 v5, 0xffff0000, v199
	v_mul_f32_e32 v244, v244, v2
	v_mul_f32_e32 v245, v245, v3
	v_mul_f32_e32 v246, v246, v4
	v_mul_f32_e32 v247, v247, v5
	v_cvt_pk_bf16_f32 v198, v244, v245
	v_cvt_pk_bf16_f32 v199, v246, v247
	s_waitcnt vmcnt(3)
	v_lshlrev_b32_e32 v2, 16, v200
	v_and_b32_e32 v3, 0xffff0000, v200
	v_lshlrev_b32_e32 v4, 16, v201
	v_and_b32_e32 v5, 0xffff0000, v201
	v_mul_f32_e32 v96, v96, v2
	v_mul_f32_e32 v97, v97, v3
	v_mul_f32_e32 v98, v98, v4
	v_mul_f32_e32 v99, v99, v5
	v_cvt_pk_bf16_f32 v200, v96, v97
	v_cvt_pk_bf16_f32 v201, v98, v99
	s_waitcnt vmcnt(2)
	v_lshlrev_b32_e32 v2, 16, v202
	v_and_b32_e32 v3, 0xffff0000, v202
	v_lshlrev_b32_e32 v4, 16, v203
	v_and_b32_e32 v5, 0xffff0000, v203
	v_mul_f32_e32 v100, v100, v2
	v_mul_f32_e32 v101, v101, v3
	v_mul_f32_e32 v102, v102, v4
	v_mul_f32_e32 v103, v103, v5
	v_cvt_pk_bf16_f32 v202, v100, v101
	v_cvt_pk_bf16_f32 v203, v102, v103
	s_waitcnt vmcnt(1)
	v_lshlrev_b32_e32 v2, 16, v216
	v_and_b32_e32 v3, 0xffff0000, v216
	v_lshlrev_b32_e32 v4, 16, v217
	v_and_b32_e32 v5, 0xffff0000, v217
	v_mul_f32_e32 v104, v104, v2
	v_mul_f32_e32 v105, v105, v3
	v_mul_f32_e32 v106, v106, v4
	v_mul_f32_e32 v107, v107, v5
	v_cvt_pk_bf16_f32 v216, v104, v105
	v_cvt_pk_bf16_f32 v217, v106, v107
	s_waitcnt vmcnt(0)
	v_lshlrev_b32_e32 v2, 16, v248
	v_and_b32_e32 v3, 0xffff0000, v248
	v_lshlrev_b32_e32 v4, 16, v249
	v_and_b32_e32 v5, 0xffff0000, v249
	v_mul_f32_e32 v108, v108, v2
	v_mul_f32_e32 v109, v109, v3
	v_mul_f32_e32 v110, v110, v4
	v_mul_f32_e32 v111, v111, v5
	v_cvt_pk_bf16_f32 v248, v108, v109
	v_cvt_pk_bf16_f32 v249, v110, v111
	global_store_dwordx2 v212, v[190:191], s[52:53] offset:0 sc0 sc1
	global_store_dwordx2 v212, v[192:193], s[52:53] offset:16 sc0 sc1
	global_store_dwordx2 v212, v[194:195], s[52:53] offset:32 sc0 sc1
	global_store_dwordx2 v212, v[198:199], s[52:53] offset:48 sc0 sc1
	global_store_dwordx2 v212, v[200:201], s[52:53] offset:64 sc0 sc1
	global_store_dwordx2 v212, v[202:203], s[52:53] offset:80 sc0 sc1
	global_store_dwordx2 v212, v[216:217], s[52:53] offset:96 sc0 sc1
	global_store_dwordx2 v212, v[248:249], s[52:53] offset:112 sc0 sc1
	s_or_b64 exec, exec, s[6:7]
	s_mov_b64 s[6:7], 0
	s_waitcnt vmcnt(0)
	s_barrier
	s_and_saveexec_b64 s[18:19], s[80:81]
	s_cbranch_execz .Lat3_smpdone
	v_mov_b32_e32 v2, 0x3900
	v_mov_b32_e32 v3, 1
	global_atomic_add v2, v3, s[78:79]
